# grid barrier v2: last arriver of each XCD adds to all per-XCD words, everyone polls own XCD word (one hop less); write-through stores, no release fence
# speedup vs baseline: 1.0423x; 1.0061x over previous
; __device__ __forceinline__ unsigned xb_ld(unsigned* p)              { return __hip_atomic_load(p, __ATOMIC_RELAXED, __HIP_MEMORY_SCOPE_AGENT); }
; __device__ __forceinline__ unsigned xb_add(unsigned* p, unsigned v) { return __hip_atomic_fetch_add(p, v, __ATOMIC_RELAXED, __HIP_MEMORY_SCOPE_AGENT); }
; #define XB_SPIN(cond, bar) do { unsigned _sp = 0; while (cond) { __builtin_amdgcn_s_sleep(1); \
;     if ((++_sp & 255u) == 0u) { if (xb_ld(&(bar)[XB_TMO])) break; if (_sp > XB_SPIN_CAP) { atomicAdd(&(bar)[XB_TMO], 1u); break; } } } } while (0)
; __device__ __forceinline__ void xcd_barrier(const XcdBarrier& b) {
;     asm volatile("s_waitcnt vmcnt(0)" ::: "memory");
;     __syncthreads();
;     if (threadIdx.x == 0) {
;         unsigned* bar = b.bar;
;         __builtin_amdgcn_s_waitcnt(0);
;         unsigned nloc = b.st[0], nx = b.st[1];
;         if (nloc == 0u) { xcd_barrier_complete(bar, b.x, nloc, nx); b.st[0] = nloc; b.st[1] = nx; }
;         const unsigned old = xb_add(&bar[XB_XSUB(b.x)], 1u);
;         const unsigned gen = old / nloc;
;         if (old + 1u == (gen + 1u) * nloc) {
;             __builtin_amdgcn_fence(__ATOMIC_RELEASE, "agent");
;             asm volatile("s_waitcnt vmcnt(0)" ::: "memory");
;             const unsigned og = xb_add(&bar[XB_TOP], 1u);
;             const unsigned tg = og / nx;
;             if (og + 1u == (tg + 1u) * nx) xb_add(&bar[XB_TOPGEN], 1u);
;             else XB_SPIN(xb_ld(&bar[XB_TOPGEN]) == tg, bar);
;             __builtin_amdgcn_fence(__ATOMIC_ACQUIRE, "agent");
;             xb_add(&bar[XB_XGEN(b.x)], 1u);
;             asm volatile("s_waitcnt vmcnt(0)" ::: "memory");
;         } else {
;             XB_SPIN(xb_ld(&bar[XB_XGEN(b.x)]) == gen, bar);
;             __builtin_amdgcn_fence(__ATOMIC_ACQUIRE, "agent");
;             asm volatile("s_waitcnt vmcnt(0)" ::: "memory");
;         }
;     }
;     __syncthreads();
; }
.LBB0_601:
	v_readlane_b32 s2, v254, 50
	v_readlane_b32 s3, v254, 51
	v_mov_b32_e32 v3, 1
	s_add_i32 s101, s101, 1
	s_waitcnt lgkmcnt(0)
	s_nop 4
	global_atomic_add v5, v99, v3, s[2:3] sc0
	v_readfirstlane_b32 s6, v4
	v_readfirstlane_b32 s7, v2
	s_mul_i32 s6, s6, s101
	s_mul_i32 s7, s7, s101
	s_add_u32 s8, s62, 0x2400
	s_addc_u32 s9, s63, 0
	v_readlane_b32 s2, v254, 52
	v_readlane_b32 s3, v254, 53
	s_mov_b32 s10, 0
	s_waitcnt vmcnt(0)
	v_readfirstlane_b32 s11, v5
	s_add_i32 s11, s11, 1
	s_cmp_lg_u32 s11, s6
	s_cbranch_scc1 .Lmy_bar_spin
	global_atomic_add v99, v3, s[8:9]
	global_atomic_add v99, v3, s[8:9] offset:256
	global_atomic_add v99, v3, s[8:9] offset:512
	global_atomic_add v99, v3, s[8:9] offset:768
	global_atomic_add v99, v3, s[8:9] offset:1024
	global_atomic_add v99, v3, s[8:9] offset:1280
	global_atomic_add v99, v3, s[8:9] offset:1536
	global_atomic_add v99, v3, s[8:9] offset:1792
	global_atomic_add v99, v3, s[8:9] offset:2048
	global_atomic_add v99, v3, s[8:9] offset:2304
	global_atomic_add v99, v3, s[8:9] offset:2560
	global_atomic_add v99, v3, s[8:9] offset:2816
	global_atomic_add v99, v3, s[8:9] offset:3072
	global_atomic_add v99, v3, s[8:9] offset:3328
	global_atomic_add v99, v3, s[8:9] offset:3584
	global_atomic_add v99, v3, s[8:9] offset:3840
.Lmy_bar_spin:
	global_load_dword v5, v99, s[2:3] sc1
	s_waitcnt vmcnt(0)
	v_readfirstlane_b32 s11, v5
	s_cmp_ge_u32 s11, s7
	s_cbranch_scc1 .Lmy_bar_done
	s_sleep 1
	s_add_i32 s10, s10, 1
	s_cmp_lt_u32 s10, 0x2000
	s_cbranch_scc1 .Lmy_bar_spin
